# row-norm passes: split-K slab fold of the tail rows issues 16 loads into distinct registers behind counted waits (was one destination quad with vmcnt(0) after every load: 64/32/16 dependent round trip
# baseline (speedup 1.0000x reference)
; __device__ __forceinline__ void norm_phase(const Params& p, const float* __restrict__ gain, int mode, int nslab) {
;     ...
;     if (nslab > 0 && r >= 32768) {
;       const float* sl = (const float*)(p.ws + OFF_SLAB) + (size_t)(r - 32768) * 1024 + lane * 4;
;       for (int sI = 0; sI < nslab; ++sI)
; #pragma unroll
;         for (int i = 0; i < 4; ++i) { const float4 a = *(const float4*)(sl + (size_t)sI * 131072 + i * 256); v[i].x += a.x; v[i].y += a.y; v[i].z += a.z; v[i].w += a.w; }
; #pragma unroll
;       for (int i = 0; i < 4; ++i) *(float4*)(hp + i * 256 + lane * 4) = v[i];
;     }
.LBB0_1032:
	v_lshl_add_u64 v[54:55], v[52:53], 0, s[6:7]
	s_add_u32 s6, s6, 0x200000
	s_addc_u32 s7, s7, 0
	v_add_co_u32_e32 v124, vcc, 0x1bb15000, v54
	s_nop 1
	v_addc_co_u32_e32 v125, vcc, 0, v55, vcc
	global_load_dwordx4 v[64:67], v[124:125], off offset:2304
	global_load_dwordx4 v[68:71], v[124:125], off offset:3328
	v_add_co_u32_e32 v124, vcc, 0x1bb16000, v54
	s_nop 1
	v_addc_co_u32_e32 v125, vcc, 0, v55, vcc
	global_load_dwordx4 v[72:75], v[124:125], off offset:256
	global_load_dwordx4 v[76:79], v[124:125], off offset:1280
	v_add_co_u32_e32 v124, vcc, 0x1bb95000, v54
	s_nop 1
	v_addc_co_u32_e32 v125, vcc, 0, v55, vcc
	global_load_dwordx4 v[80:83], v[124:125], off offset:2304
	global_load_dwordx4 v[84:87], v[124:125], off offset:3328
	v_add_co_u32_e32 v124, vcc, 0x1bb96000, v54
	s_nop 1
	v_addc_co_u32_e32 v125, vcc, 0, v55, vcc
	global_load_dwordx4 v[88:91], v[124:125], off offset:256
	global_load_dwordx4 v[92:95], v[124:125], off offset:1280
	v_add_co_u32_e32 v124, vcc, 0x1bc15000, v54
	s_nop 1
	v_addc_co_u32_e32 v125, vcc, 0, v55, vcc
	global_load_dwordx4 v[96:99], v[124:125], off offset:2304
	global_load_dwordx4 v[100:103], v[124:125], off offset:3328
	v_add_co_u32_e32 v124, vcc, 0x1bc16000, v54
	s_nop 1
	v_addc_co_u32_e32 v125, vcc, 0, v55, vcc
	global_load_dwordx4 v[104:107], v[124:125], off offset:256
	global_load_dwordx4 v[108:111], v[124:125], off offset:1280
	v_add_co_u32_e32 v124, vcc, 0x1bc95000, v54
	s_nop 1
	v_addc_co_u32_e32 v125, vcc, 0, v55, vcc
	global_load_dwordx4 v[112:115], v[124:125], off offset:2304
	global_load_dwordx4 v[116:119], v[124:125], off offset:3328
	v_add_co_u32_e32 v124, vcc, 0x1bc96000, v54
	s_nop 1
	v_addc_co_u32_e32 v125, vcc, 0, v55, vcc
	global_load_dwordx4 v[120:123], v[124:125], off offset:256
	s_waitcnt vmcnt(14)
	v_pk_add_f32 v[32:33], v[32:33], v[64:65]
	v_pk_add_f32 v[34:35], v[34:35], v[66:67]
	global_load_dwordx4 v[64:67], v[124:125], off offset:1280
	s_waitcnt vmcnt(14)
	v_pk_add_f32 v[28:29], v[28:29], v[68:69]
	v_pk_add_f32 v[30:31], v[30:31], v[70:71]
	s_waitcnt vmcnt(13)
	v_pk_add_f32 v[24:25], v[24:25], v[72:73]
	v_pk_add_f32 v[26:27], v[26:27], v[74:75]
	s_waitcnt vmcnt(12)
	v_pk_add_f32 v[20:21], v[20:21], v[76:77]
	v_pk_add_f32 v[22:23], v[22:23], v[78:79]
	s_waitcnt vmcnt(11)
	v_pk_add_f32 v[32:33], v[32:33], v[80:81]
	v_pk_add_f32 v[34:35], v[34:35], v[82:83]
	s_waitcnt vmcnt(10)
	v_pk_add_f32 v[28:29], v[28:29], v[84:85]
	v_pk_add_f32 v[30:31], v[30:31], v[86:87]
	s_waitcnt vmcnt(9)
	v_pk_add_f32 v[24:25], v[24:25], v[88:89]
	v_pk_add_f32 v[26:27], v[26:27], v[90:91]
	s_waitcnt vmcnt(8)
	v_pk_add_f32 v[20:21], v[20:21], v[92:93]
	v_pk_add_f32 v[22:23], v[22:23], v[94:95]
	s_waitcnt vmcnt(7)
	v_pk_add_f32 v[32:33], v[32:33], v[96:97]
	v_pk_add_f32 v[34:35], v[34:35], v[98:99]
	s_waitcnt vmcnt(6)
	v_pk_add_f32 v[28:29], v[28:29], v[100:101]
	v_pk_add_f32 v[30:31], v[30:31], v[102:103]
	s_waitcnt vmcnt(5)
	v_pk_add_f32 v[24:25], v[24:25], v[104:105]
	v_pk_add_f32 v[26:27], v[26:27], v[106:107]
	s_waitcnt vmcnt(4)
	v_pk_add_f32 v[20:21], v[20:21], v[108:109]
	v_pk_add_f32 v[22:23], v[22:23], v[110:111]
	s_waitcnt vmcnt(3)
	v_pk_add_f32 v[32:33], v[32:33], v[112:113]
	v_pk_add_f32 v[34:35], v[34:35], v[114:115]
	s_waitcnt vmcnt(2)
	v_pk_add_f32 v[28:29], v[28:29], v[116:117]
	v_pk_add_f32 v[30:31], v[30:31], v[118:119]
	s_waitcnt vmcnt(1)
	v_pk_add_f32 v[24:25], v[24:25], v[120:121]
	v_pk_add_f32 v[26:27], v[26:27], v[122:123]
	s_waitcnt vmcnt(0)
	v_pk_add_f32 v[20:21], v[20:21], v[64:65]
	v_pk_add_f32 v[22:23], v[22:23], v[66:67]
	s_cmp_eq_u32 s6, 0x800000
	s_cbranch_scc0 .LBB0_1032
	v_lshlrev_b64 v[48:49], 12, v[48:49]
	v_lshl_add_u64 v[48:49], v[50:51], 0, v[48:49]
	v_mov_b32_e32 v45, v130
	v_lshl_add_u64 v[48:49], v[48:49], 0, v[44:45]
	global_store_dwordx4 v[48:49], v[32:35], off
	global_store_dwordx4 v[48:49], v[28:31], off offset:1024
	global_store_dwordx4 v[48:49], v[24:27], off offset:2048
	global_store_dwordx4 v[48:49], v[20:23], off offset:3072
	s_branch .LBB0_1019
